# sample-row mini-GEMMs fully LDS-staged: both operands loaded with row-contiguous full-line global loads (shared operand once per workgroup, double-buffered; per-wave operand in wave-private LDS) and r
# speedup vs baseline: 1.0820x; 1.0142x over previous
; __device__ __forceinline__ int tidx() { int t = (int)__builtin_amdgcn_workitem_id_x(); asm volatile("" : "+v"(t)); return t; }
; __device__ __forceinline__ unsigned cvt_pk_bf16(float lo, float hi) { unsigned r; asm("v_cvt_pk_bf16_f32 %0, %1, %2" : "=v"(r) : "v"(lo), "v"(hi)); return r; }
; __device__ __forceinline__ float sigm(float x) { return rcpf_(1.f + __expf(-x)); }
; __device__ __forceinline__ float lo_bf(unsigned w) { return __uint_as_float(w << 16); }
; __device__ __forceinline__ f32x4 mini_tile(const bf16_t* __restrict__ A, const bf16_t* __restrict__ Bt, int K, int m0, int n0, int lane) {
;     const bf16_t* ap = A + (size_t)(m0 + (lane & 15)) * K + 8 * (lane >> 4);
;     const bf16_t* bp = Bt + (size_t)(n0 + (lane & 15)) * K + 8 * (lane >> 4);
;     f32x4 acc0 = (f32x4){0.f, 0.f, 0.f, 0.f}, acc1 = (f32x4){0.f, 0.f, 0.f, 0.f};
; #pragma unroll 1
;     for (int k0 = 0; k0 < K; k0 += 256) {
;         bf16x8 a[8], b[8];
; #pragma unroll
;         for (int i = 0; i < 8; ++i) { a[i] = *(const bf16x8*)(ap + k0 + 32 * i); b[i] = *(const bf16x8*)(bp + k0 + 32 * i); }
; #pragma unroll
;         for (int i = 0; i < 8; i += 2) { acc0 = __builtin_amdgcn_mfma_f32_16x16x32_bf16(b[i], a[i], acc0, 0, 0, 0); acc1 = __builtin_amdgcn_mfma_f32_16x16x32_bf16(b[i + 1], a[i + 1], acc1, 0, 0, 0); }
;     }
;     return acc0 + acc1;
; }
; __device__ __forceinline__ void mini_branch(const Params& p, int l, int bid, int nblk) {
;     const int tid = tidx(), wid = tid >> 6, lane = tid & 63, g = lane >> 4;
;     for (int s = bid; s < 256; s += nblk) {
;         const int m0 = SEQ + 16 * (s >> 3), n0 = 128 * (s & 7) + 16 * wid, m = m0 + (lane & 15), n = n0 + 4 * g;
;         f32x4 val = (f32x4){0.f, 0.f, 0.f, 0.f};
; #pragma unroll 1
;         for (int z = 0; z < 3; ++z) {
;             const f32x4 acc = mini_tile(p.Y + (size_t)z * MROWS * 1024, p.WbrT + (size_t)(l * 3 + z) * 1048576, 1024, m0, n0, lane);
;             const u32x2 gw = *(const u32x2*)(p.P + (size_t)m * NIN + C_GM + z * 1024 + n);
;             val[0] += sigm(lo_bf(gw.x)) * acc[0]; val[1] += sigm(hi_bf(gw.x)) * acc[1]; val[2] += sigm(lo_bf(gw.y)) * acc[2]; val[3] += sigm(hi_bf(gw.y)) * acc[3];
;         }
;         u32x2 w; w.x = cvt_pk_bf16(val[0], val[1]); w.y = cvt_pk_bf16(val[2], val[3]);
;         *(u32x2*)(p.merged + (size_t)m * 1024 + n) = w;
.LBB0_220:
	s_movk_i32 s16, 0xff00
	v_mov_b64_e32 v[24:25], v[14:15]
	v_mov_b64_e32 v[26:27], v[10:11]
	v_mov_b32_e32 v0, 0
	v_mov_b32_e32 v1, v32
	v_mov_b32_e32 v2, v32
	v_mov_b32_e32 v3, v32
	s_waitcnt vmcnt(0)
	v_mov_b32_e32 v6, 0
	v_mov_b32_e32 v7, v32
	v_mov_b32_e32 v8, v32
	v_mov_b32_e32 v9, v32
	v_and_b32_e32 v160, 63, v234
	v_lshrrev_b32_e32 v161, 5, v160
	v_and_b32_e32 v162, 15, v160
	v_and_b32_e32 v164, 31, v160
	v_lshlrev_b32_e32 v164, 4, v164
	v_mov_b32_e32 v165, 0
	v_lshrrev_b32_e32 v163, 6, v234
	v_sub_u32_e32 v166, v161, v162
	v_lshlrev_b32_e32 v166, 11, v166
	v_ashrrev_i32_e32 v167, 31, v166
	v_lshl_add_u64 v[166:167], v[166:167], 0, v[164:165]
	v_lshl_add_u64 v[144:145], v[166:167], 0, v[26:27]
	s_mov_b32 s99, 0
	s_mov_b32 s98, 0x1000
	v_lshl_add_u64 v[146:147], v[144:145], 0, s[98:99]
	v_lshl_add_u64 v[148:149], v[146:147], 0, s[98:99]
	v_lshl_add_u64 v[150:151], v[148:149], 0, s[98:99]
	v_lshl_add_u64 v[152:153], v[150:151], 0, s[98:99]
	v_lshl_add_u64 v[154:155], v[152:153], 0, s[98:99]
	v_lshl_add_u64 v[156:157], v[154:155], 0, s[98:99]
	v_lshl_add_u64 v[158:159], v[156:157], 0, s[98:99]
	v_lshl_add_u32 v166, v163, 1, v161
	v_mul_u32_u24_e32 v110, 0x210, v166
	v_add_u32_e32 v110, v110, v164
	v_sub_u32_e32 v166, v166, v162
	v_lshlrev_b32_e32 v166, 11, v166
	v_ashrrev_i32_e32 v167, 31, v166
	v_lshl_add_u64 v[166:167], v[166:167], 0, v[164:165]
	v_lshl_add_u64 v[102:103], v[166:167], 0, v[24:25]
	v_lshrrev_b32_e32 v166, 4, v160
	v_lshlrev_b32_e32 v166, 4, v166
	v_mul_u32_u24_e32 v111, 0x210, v162
	v_add_u32_e32 v111, v111, v166
	v_mul_u32_u24_e32 v167, 0x2100, v163
	v_add_u32_e32 v167, 0x8000, v167
	v_add_u32_e32 v105, v111, v167
	v_mul_u32_u24_e32 v104, 0x210, v161
	v_add3_u32 v104, v104, v164, v167
.LBB0_221:
	global_load_dwordx4 v[106:109], v[102:103], off
	global_load_dwordx4 v[112:115], v[144:145], off
	global_load_dwordx4 v[116:119], v[146:147], off
	global_load_dwordx4 v[120:123], v[148:149], off
	global_load_dwordx4 v[124:127], v[150:151], off
	global_load_dwordx4 v[128:131], v[152:153], off
	global_load_dwordx4 v[132:135], v[154:155], off
	global_load_dwordx4 v[136:139], v[156:157], off
	global_load_dwordx4 v[140:143], v[158:159], off
	s_addk_i32 s16, 0x100
	v_lshl_add_u64 v[26:27], v[26:27], 0, s[54:55]
	s_cmpk_lt_u32 s16, 0x300
	v_lshl_add_u64 v[24:25], v[24:25], 0, s[54:55]
	v_lshl_add_u64 v[102:103], v[102:103], 0, s[54:55]
	v_lshl_add_u64 v[144:145], v[144:145], 0, s[54:55]
	v_lshl_add_u64 v[146:147], v[146:147], 0, s[54:55]
	v_lshl_add_u64 v[148:149], v[148:149], 0, s[54:55]
	v_lshl_add_u64 v[150:151], v[150:151], 0, s[54:55]
	v_lshl_add_u64 v[152:153], v[152:153], 0, s[54:55]
	v_lshl_add_u64 v[154:155], v[154:155], 0, s[54:55]
	v_lshl_add_u64 v[156:157], v[156:157], 0, s[54:55]
	v_lshl_add_u64 v[158:159], v[158:159], 0, s[54:55]
	s_waitcnt vmcnt(8)
	ds_write_b128 v110, v[106:109]
	s_waitcnt vmcnt(7)
	ds_write_b128 v104, v[112:115]
	s_waitcnt vmcnt(6)
	ds_write_b128 v104, v[116:119] offset:1056
	s_waitcnt vmcnt(5)
	ds_write_b128 v104, v[120:123] offset:2112
	s_waitcnt vmcnt(4)
	ds_write_b128 v104, v[124:127] offset:3168
	s_waitcnt vmcnt(3)
	ds_write_b128 v104, v[128:131] offset:4224
	s_waitcnt vmcnt(2)
	ds_write_b128 v104, v[132:135] offset:5280
	s_waitcnt vmcnt(1)
	ds_write_b128 v104, v[136:139] offset:6336
	s_waitcnt vmcnt(0)
	ds_write_b128 v104, v[140:143] offset:7392
	s_waitcnt lgkmcnt(0)
	s_barrier
	ds_read_b128 v[42:45], v111
	ds_read_b128 v[34:37], v105
	ds_read_b128 v[46:49], v111 offset:64
	ds_read_b128 v[38:41], v105 offset:64
	ds_read_b128 v[54:57], v111 offset:128
	ds_read_b128 v[50:53], v105 offset:128
	ds_read_b128 v[62:65], v111 offset:192
	ds_read_b128 v[58:61], v105 offset:192
	ds_read_b128 v[74:77], v111 offset:256
	ds_read_b128 v[70:73], v105 offset:256
	ds_read_b128 v[82:85], v111 offset:320
	ds_read_b128 v[78:81], v105 offset:320
	ds_read_b128 v[90:93], v111 offset:384
	ds_read_b128 v[86:89], v105 offset:384
	ds_read_b128 v[98:101], v111 offset:448
	ds_read_b128 v[94:97], v105 offset:448
	v_xor_b32_e32 v110, 0x4000, v110
	v_xor_b32_e32 v111, 0x4000, v111
	s_waitcnt lgkmcnt(14)
	v_mfma_f32_16x16x32_bf16 v[0:3], v[34:37], v[42:45], v[0:3]
	s_waitcnt lgkmcnt(12)
	v_mfma_f32_16x16x32_bf16 v[6:9], v[38:41], v[46:49], v[6:9]
	s_waitcnt lgkmcnt(10)
	v_mfma_f32_16x16x32_bf16 v[0:3], v[50:53], v[54:57], v[0:3]
	s_waitcnt lgkmcnt(8)
	v_mfma_f32_16x16x32_bf16 v[6:9], v[58:61], v[62:65], v[6:9]
	s_waitcnt lgkmcnt(6)
	v_mfma_f32_16x16x32_bf16 v[0:3], v[70:73], v[74:77], v[0:3]
	s_waitcnt lgkmcnt(4)
	v_mfma_f32_16x16x32_bf16 v[6:9], v[78:81], v[82:85], v[6:9]
	s_waitcnt lgkmcnt(2)
	v_mfma_f32_16x16x32_bf16 v[0:3], v[86:89], v[90:93], v[0:3]
	s_waitcnt lgkmcnt(0)
	v_mfma_f32_16x16x32_bf16 v[6:9], v[94:97], v[98:101], v[6:9]
	s_cbranch_scc1 .LBB0_221
	s_lshl_b32 s50, s9, 11
	v_lshl_add_u64 v[24:25], v[18:19], 0, s[50:51]
	global_load_dwordx2 v[24:25], v[24:25], off
	s_nop 3
	v_pk_add_f32 v[2:3], v[2:3], v[8:9]
	v_pk_add_f32 v[0:1], v[0:1], v[6:7]
	s_add_i32 s9, s9, 1
	s_mov_b64 s[16:17], 0x200000
	v_lshl_add_u64 v[10:11], v[10:11], 0, s[16:17]
	s_cmp_eq_u32 s9, 3
	v_lshl_add_u64 v[14:15], v[14:15], 0, s[60:61]
	s_waitcnt vmcnt(0)
	v_lshlrev_b32_e32 v6, 16, v24
	v_and_b32_e32 v7, 0xffff0000, v24
	v_lshlrev_b32_e32 v8, 16, v25
	v_and_b32_e32 v9, 0xffff0000, v25
	v_mul_f32_e32 v6, 0xbfb8aa3b, v6
	v_mul_f32_e32 v7, 0xbfb8aa3b, v7
	v_mul_f32_e32 v8, 0xbfb8aa3b, v8
	v_mul_f32_e32 v9, 0xbfb8aa3b, v9
	v_exp_f32_e32 v6, v6
	v_exp_f32_e32 v7, v7
	v_exp_f32_e32 v8, v8
	v_exp_f32_e32 v9, v9
	v_add_f32_e32 v6, 1.0, v6
	v_add_f32_e32 v7, 1.0, v7
	v_add_f32_e32 v8, 1.0, v8
	v_add_f32_e32 v9, 1.0, v9
	v_rcp_f32_e32 v6, v6
	v_rcp_f32_e32 v7, v7
	v_rcp_f32_e32 v8, v8
	v_rcp_f32_e32 v9, v9
	v_pk_fma_f32 v[22:23], v[0:1], v[6:7], v[22:23]
	v_pk_fma_f32 v[20:21], v[2:3], v[8:9], v[20:21]
	s_cbranch_scc0 .LBB0_220
	v_lshlrev_b64 v[0:1], 11, v[16:17]
	v_lshl_add_u64 v[0:1], s[18:19], 0, v[0:1]
	s_add_i32 s8, s8, s42
	s_add_i32 s4, s4, s5
	s_add_i32 s6, s6, s7
	v_lshl_add_u64 v[0:1], v[12:13], 1, v[0:1]
	s_cmpk_gt_i32 s8, 0xff
	v_cvt_pk_bf16_f32 v2, v22, v23
	v_cvt_pk_bf16_f32 v3, v20, v21
	global_store_dwordx2 v[0:1], v[2:3], off
	s_cbranch_scc0 .LBB0_219

; __device__ __forceinline__ f32x4 mini_tile(const bf16_t* __restrict__ A, const bf16_t* __restrict__ Bt, int K, int m0, int n0, int lane) {
;     const bf16_t* ap = A + (size_t)(m0 + (lane & 15)) * K + 8 * (lane >> 4);
;     const bf16_t* bp = Bt + (size_t)(n0 + (lane & 15)) * K + 8 * (lane >> 4);
;     f32x4 acc0 = (f32x4){0.f, 0.f, 0.f, 0.f}, acc1 = (f32x4){0.f, 0.f, 0.f, 0.f};
; #pragma unroll 1
;     for (int k0 = 0; k0 < K; k0 += 256) {
;         bf16x8 a[8], b[8];
; #pragma unroll
;         for (int i = 0; i < 8; ++i) { a[i] = *(const bf16x8*)(ap + k0 + 32 * i); b[i] = *(const bf16x8*)(bp + k0 + 32 * i); }
; #pragma unroll
;         for (int i = 0; i < 8; i += 2) { acc0 = __builtin_amdgcn_mfma_f32_16x16x32_bf16(b[i], a[i], acc0, 0, 0, 0); acc1 = __builtin_amdgcn_mfma_f32_16x16x32_bf16(b[i + 1], a[i + 1], acc1, 0, 0, 0); }
;     }
;     return acc0 + acc1;
; }
; __device__ __forceinline__ void mini_branch(const Params& p, int l, int bid, int nblk) {
;     const int tid = tidx(), wid = tid >> 6, lane = tid & 63, g = lane >> 4;
;     for (int s = bid; s < 256; s += nblk) {
;         const int m0 = SEQ + 16 * (s >> 3), n0 = 128 * (s & 7) + 16 * wid, m = m0 + (lane & 15), n = n0 + 4 * g;
;         f32x4 val = (f32x4){0.f, 0.f, 0.f, 0.f};
; #pragma unroll 1
;         for (int z = 0; z < 3; ++z) {
;             const f32x4 acc = mini_tile(p.Y + (size_t)z * MROWS * 1024, p.WbrT + (size_t)(l * 3 + z) * 1048576, 1024, m0, n0, lane);
;             const u32x2 gw = *(const u32x2*)(p.P + (size_t)m * NIN + C_GM + z * 1024 + n);
;             val[0] += sigm(lo_bf(gw.x)) * acc[0]; val[1] += sigm(hi_bf(gw.x)) * acc[1]; val[2] += sigm(lo_bf(gw.y)) * acc[2]; val[3] += sigm(hi_bf(gw.y)) * acc[3];
;         }
;         u32x2 w; w.x = cvt_pk_bf16(val[0], val[1]); w.y = cvt_pk_bf16(val[2], val[3]);
;         *(u32x2*)(p.merged + (size_t)m * 1024 + n) = w;
;     }
; }
; __device__ __forceinline__ void mini_res(const float* Xin, float* Xo, bf16_t* Xbo, const bf16_t* A, const bf16_t* Bt, int K, float* sumsq, int bid, int nblk) {
;     const int tid = tidx(), wid = tid >> 6, lane = tid & 63, g = lane >> 4;
;     for (int s = bid; s < 256; s += nblk) {
;         const int m0 = SEQ + 16 * (s >> 3), n0 = 128 * (s & 7) + 16 * wid, m = m0 + (lane & 15), n = n0 + 4 * g;
;         const f32x4 acc = mini_tile(A, Bt, K, m0, n0, lane);
;         float* xp = Xo + (size_t)m * 1024 + n;
.LBB0_801:
	s_and_b32 s4, s9, 0x380
	v_add_u32_e32 v2, s4, v17
	s_waitcnt lgkmcnt(0)
	v_mov_b64_e32 v[0:1], s[14:15]
	v_mad_i64_i32 v[10:11], s[4:5], s8, v2, v[0:1]
	s_and_b32 s4, s11, -16
	s_nop 0
	v_add_u32_e32 v2, s4, v16
	v_mov_b64_e32 v[0:1], s[20:21]
	v_mad_i64_i32 v[12:13], s[4:5], s8, v2, v[0:1]
	v_mov_b32_e32 v0, 0
	s_mov_b32 s4, 0
	v_mov_b32_e32 v1, v0
	v_mov_b32_e32 v2, v0
	v_mov_b32_e32 v3, v0
	s_waitcnt vmcnt(8)
	v_mov_b32_e32 v6, v0
	v_mov_b32_e32 v7, v0
	v_mov_b32_e32 v8, v0
	v_mov_b32_e32 v9, v0
	v_and_b32_e32 v144, 63, v234
	v_lshrrev_b32_e32 v145, 5, v144
	v_and_b32_e32 v146, 15, v144
	v_and_b32_e32 v148, 31, v144
	v_lshlrev_b32_e32 v148, 4, v148
	v_mov_b32_e32 v149, 0
	v_lshrrev_b32_e32 v147, 6, v234
	v_sub_u32_e32 v150, v145, v146
	v_mul_lo_u32 v150, v150, s8
	v_ashrrev_i32_e32 v151, 31, v150
	v_lshl_add_u64 v[150:151], v[150:151], 0, v[148:149]
	v_lshl_add_u64 v[128:129], v[150:151], 0, v[10:11]
	s_mov_b32 s99, 0
	s_lshl_b32 s98, s8, 1
	v_lshl_add_u64 v[130:131], v[128:129], 0, s[98:99]
	v_lshl_add_u64 v[132:133], v[130:131], 0, s[98:99]
	v_lshl_add_u64 v[134:135], v[132:133], 0, s[98:99]
	v_lshl_add_u64 v[136:137], v[134:135], 0, s[98:99]
	v_lshl_add_u64 v[138:139], v[136:137], 0, s[98:99]
	v_lshl_add_u64 v[140:141], v[138:139], 0, s[98:99]
	v_lshl_add_u64 v[142:143], v[140:141], 0, s[98:99]
	v_lshl_add_u32 v150, v147, 1, v145
	v_mul_u32_u24_e32 v94, 0x210, v150
	v_add_u32_e32 v94, v94, v148
	v_sub_u32_e32 v150, v150, v146
	v_mul_lo_u32 v150, v150, s8
	v_ashrrev_i32_e32 v151, 31, v150
	v_lshl_add_u64 v[150:151], v[150:151], 0, v[148:149]
	v_lshl_add_u64 v[86:87], v[150:151], 0, v[12:13]
	v_lshrrev_b32_e32 v150, 4, v144
	v_lshlrev_b32_e32 v150, 4, v150
	v_mul_u32_u24_e32 v95, 0x210, v146
	v_add_u32_e32 v95, v95, v150
	v_mul_u32_u24_e32 v151, 0x2100, v147
	v_add_u32_e32 v151, 0x8000, v151
	v_add_u32_e32 v89, v95, v151
	v_mul_u32_u24_e32 v88, 0x210, v145
	v_add3_u32 v88, v88, v148, v151
.LBB0_802:
	global_load_dwordx4 v[90:93], v[86:87], off
	global_load_dwordx4 v[96:99], v[128:129], off
	global_load_dwordx4 v[100:103], v[130:131], off
	global_load_dwordx4 v[104:107], v[132:133], off
	global_load_dwordx4 v[108:111], v[134:135], off
	global_load_dwordx4 v[112:115], v[136:137], off
	global_load_dwordx4 v[116:119], v[138:139], off
	global_load_dwordx4 v[120:123], v[140:141], off
	global_load_dwordx4 v[124:127], v[142:143], off
	s_addk_i32 s4, 0x100
	v_lshl_add_u64 v[10:11], v[10:11], 0, s[54:55]
	s_cmp_lt_u32 s4, s49
	v_lshl_add_u64 v[12:13], v[12:13], 0, s[54:55]
	v_lshl_add_u64 v[86:87], v[86:87], 0, s[54:55]
	v_lshl_add_u64 v[128:129], v[128:129], 0, s[54:55]
	v_lshl_add_u64 v[130:131], v[130:131], 0, s[54:55]
	v_lshl_add_u64 v[132:133], v[132:133], 0, s[54:55]
	v_lshl_add_u64 v[134:135], v[134:135], 0, s[54:55]
	v_lshl_add_u64 v[136:137], v[136:137], 0, s[54:55]
	v_lshl_add_u64 v[138:139], v[138:139], 0, s[54:55]
	v_lshl_add_u64 v[140:141], v[140:141], 0, s[54:55]
	v_lshl_add_u64 v[142:143], v[142:143], 0, s[54:55]
	s_waitcnt vmcnt(8)
	ds_write_b128 v94, v[90:93]
	s_waitcnt vmcnt(7)
	ds_write_b128 v88, v[96:99]
	s_waitcnt vmcnt(6)
	ds_write_b128 v88, v[100:103] offset:1056
	s_waitcnt vmcnt(5)
	ds_write_b128 v88, v[104:107] offset:2112
	s_waitcnt vmcnt(4)
	ds_write_b128 v88, v[108:111] offset:3168
	s_waitcnt vmcnt(3)
	ds_write_b128 v88, v[112:115] offset:4224
	s_waitcnt vmcnt(2)
	ds_write_b128 v88, v[116:119] offset:5280
	s_waitcnt vmcnt(1)
	ds_write_b128 v88, v[120:123] offset:6336
	s_waitcnt vmcnt(0)
	ds_write_b128 v88, v[124:127] offset:7392
	s_waitcnt lgkmcnt(0)
	s_barrier
	ds_read_b128 v[22:25], v95
	ds_read_b128 v[18:21], v89
	ds_read_b128 v[30:33], v95 offset:64
	ds_read_b128 v[26:29], v89 offset:64
	ds_read_b128 v[38:41], v95 offset:128
	ds_read_b128 v[34:37], v89 offset:128
	ds_read_b128 v[50:53], v95 offset:192
	ds_read_b128 v[42:45], v89 offset:192
	ds_read_b128 v[58:61], v95 offset:256
	ds_read_b128 v[54:57], v89 offset:256
	ds_read_b128 v[66:69], v95 offset:320
	ds_read_b128 v[62:65], v89 offset:320
	ds_read_b128 v[74:77], v95 offset:384
	ds_read_b128 v[70:73], v89 offset:384
	ds_read_b128 v[82:85], v95 offset:448
	ds_read_b128 v[78:81], v89 offset:448
	v_xor_b32_e32 v94, 0x4000, v94
	v_xor_b32_e32 v95, 0x4000, v95
	s_waitcnt lgkmcnt(14)
	v_mfma_f32_16x16x32_bf16 v[0:3], v[18:21], v[22:25], v[0:3]
	s_waitcnt lgkmcnt(12)
	v_mfma_f32_16x16x32_bf16 v[6:9], v[26:29], v[30:33], v[6:9]
	s_waitcnt lgkmcnt(10)
	v_mfma_f32_16x16x32_bf16 v[0:3], v[34:37], v[38:41], v[0:3]
	s_waitcnt lgkmcnt(8)
	v_mfma_f32_16x16x32_bf16 v[6:9], v[42:45], v[50:53], v[6:9]
	s_waitcnt lgkmcnt(6)
	v_mfma_f32_16x16x32_bf16 v[0:3], v[54:57], v[58:61], v[0:3]
	s_waitcnt lgkmcnt(4)
	v_mfma_f32_16x16x32_bf16 v[6:9], v[62:65], v[66:69], v[6:9]
	s_waitcnt lgkmcnt(2)
	v_mfma_f32_16x16x32_bf16 v[0:3], v[70:73], v[74:77], v[0:3]
	s_waitcnt lgkmcnt(0)
	v_mfma_f32_16x16x32_bf16 v[6:9], v[78:81], v[82:85], v[6:9]
	s_cbranch_scc1 .LBB0_802
	s_lshl_b32 s4, s13, 1
	s_lshl_b32 s5, s13, 7
	s_and_b32 s4, s4, -16
	s_and_b32 s5, s5, 0x380
	v_add_u32_e32 v12, s5, v14
	v_add_u32_e32 v10, s4, v16
	v_ashrrev_i32_e32 v11, 31, v10
	v_or_b32_e32 v12, v12, v15
	v_pk_add_f32 v[6:7], v[0:1], v[6:7]
	v_lshlrev_b64 v[0:1], 12, v[10:11]
	v_ashrrev_i32_e32 v13, 31, v12
	v_pk_add_f32 v[8:9], v[2:3], v[8:9]
	v_lshl_add_u64 v[2:3], s[16:17], 0, v[0:1]
	v_lshlrev_b64 v[18:19], 2, v[12:13]
	v_lshl_add_u64 v[0:1], s[6:7], 0, v[0:1]
	v_lshl_add_u64 v[0:1], v[0:1], 0, v[18:19]
	v_lshl_add_u64 v[20:21], v[2:3], 0, v[18:19]
	global_load_dwordx4 v[0:3], v[0:1], off
	s_waitcnt vmcnt(0)
	v_pk_add_f32 v[2:3], v[8:9], v[2:3]
	v_pk_add_f32 v[0:1], v[6:7], v[0:1]
	global_store_dwordx4 v[20:21], v[0:3], off
	v_cvt_pk_bf16_f32 v6, v0, v1
	v_cvt_pk_bf16_f32 v7, v2, v3
	v_lshlrev_b64 v[8:9], 11, v[10:11]
	v_lshl_add_u64 v[8:9], s[18:19], 0, v[8:9]
	v_mul_f32_e32 v1, v1, v1
	v_fmac_f32_e32 v1, v0, v0
	v_mul_f32_e32 v0, v3, v3
	v_fmac_f32_e32 v0, v2, v2
	v_and_b32_e32 v2, 64, v240
	v_add_f32_e32 v0, v1, v0
	v_xor_b32_e32 v1, 16, v240
	v_add_u32_e32 v2, 64, v2
	v_cmp_lt_i32_e64 s[4:5], v1, v2
	v_lshl_add_u64 v[8:9], v[12:13], 1, v[8:9]
	global_store_dwordx2 v[8:9], v[6:7], off
	v_cndmask_b32_e64 v1, v240, v1, s[4:5]
	v_lshlrev_b32_e32 v1, 2, v1
	ds_bpermute_b32 v1, v1, v0
	s_waitcnt lgkmcnt(0)
	v_add_f32_e32 v0, v0, v1
	v_xor_b32_e32 v1, 32, v240
	v_cmp_lt_i32_e64 s[4:5], v1, v2
	s_nop 1
	v_cndmask_b32_e64 v1, v240, v1, s[4:5]
	v_lshlrev_b32_e32 v1, 2, v1
	ds_bpermute_b32 v1, v1, v0
	s_and_saveexec_b64 s[4:5], vcc
	s_cbranch_execz .LBB0_800
	s_waitcnt lgkmcnt(0)
	v_add_f32_e32 v2, v0, v1
	v_lshl_add_u64 v[0:1], v[10:11], 2, s[22:23]
	global_atomic_add_f32 v[0:1], v2, off
	s_branch .LBB0_800
